# grid barrier: local workgroups poll the cross-XCD release word directly instead of a per-XCD word re-published by the XCD leader (one memory round trip less per barrier)
# speedup vs baseline: 1.0061x; 1.0061x over previous
.LBB0_73:
	s_or_b64 exec, exec, s[12:13]
	v_cvt_f32_u32_e32 v4, v2
	s_waitcnt vmcnt(0)
	v_readfirstlane_b32 s3, v3
	v_sub_u32_e32 v3, 0, v2
	v_rcp_iflag_f32_e32 v4, v4
	v_add_u32_e32 v5, s3, v1
	v_mul_f32_e32 v4, 0x4f7ffffe, v4
	v_cvt_u32_f32_e32 v4, v4
	v_mul_lo_u32 v1, v3, v4
	v_mul_hi_u32 v1, v4, v1
	v_add_u32_e32 v1, v4, v1
	v_mul_hi_u32 v1, v5, v1
	v_mul_lo_u32 v3, v1, v2
	v_sub_u32_e32 v3, v5, v3
	v_add_u32_e32 v4, 1, v1
	v_cmp_ge_u32_e32 vcc, v3, v2
	s_nop 1
	v_cndmask_b32_e32 v1, v1, v4, vcc
	v_sub_u32_e32 v4, v3, v2
	v_cndmask_b32_e32 v3, v3, v4, vcc
	v_add_u32_e32 v4, 1, v1
	v_cmp_ge_u32_e32 vcc, v3, v2
	v_add_u32_e32 v3, 1, v5
	s_nop 0
	v_cndmask_b32_e32 v1, v1, v4, vcc
	v_mul_lo_u32 v4, v2, v1
	v_add_u32_e32 v2, v4, v2
	v_cmp_ne_u32_e32 vcc, v3, v2
	s_and_saveexec_b64 s[10:11], vcc
	s_xor_b64 s[10:11], exec, s[10:11]
	s_cbranch_execz .LBB0_87
	s_waitcnt lgkmcnt(0)
	v_mov_b32_e32 v0, 0x7500
	global_load_dword v0, v0, s[96:97] sc1
	s_add_u32 s16, s96, 0x7500
	s_addc_u32 s17, s97, 0
	s_waitcnt vmcnt(0)
	v_cmp_eq_u32_e32 vcc, v0, v1
	s_and_saveexec_b64 s[12:13], vcc
	s_cbranch_execz .LBB0_86
	s_add_u32 s14, s96, 0x4200
	s_addc_u32 s15, s97, 0
	s_mov_b32 s3, 1
	s_mov_b64 s[18:19], 0
	v_mov_b32_e32 v0, 0
	s_branch .LBB0_77

.LBB0_401:
	s_or_b64 exec, exec, s[12:13]
	v_cvt_f32_u32_e32 v4, v2
	s_waitcnt vmcnt(0)
	v_readfirstlane_b32 s3, v3
	v_sub_u32_e32 v3, 0, v2
	v_rcp_iflag_f32_e32 v4, v4
	v_add_u32_e32 v5, s3, v1
	v_mul_f32_e32 v4, 0x4f7ffffe, v4
	v_cvt_u32_f32_e32 v4, v4
	v_mul_lo_u32 v1, v3, v4
	v_mul_hi_u32 v1, v4, v1
	v_add_u32_e32 v1, v4, v1
	v_mul_hi_u32 v1, v5, v1
	v_mul_lo_u32 v3, v1, v2
	v_sub_u32_e32 v3, v5, v3
	v_add_u32_e32 v4, 1, v1
	v_cmp_ge_u32_e32 vcc, v3, v2
	s_nop 1
	v_cndmask_b32_e32 v1, v1, v4, vcc
	v_sub_u32_e32 v4, v3, v2
	v_cndmask_b32_e32 v3, v3, v4, vcc
	v_add_u32_e32 v4, 1, v1
	v_cmp_ge_u32_e32 vcc, v3, v2
	v_add_u32_e32 v3, 1, v5
	s_nop 0
	v_cndmask_b32_e32 v1, v1, v4, vcc
	v_mul_lo_u32 v4, v2, v1
	v_add_u32_e32 v2, v4, v2
	v_cmp_ne_u32_e32 vcc, v3, v2
	s_and_saveexec_b64 s[10:11], vcc
	s_xor_b64 s[10:11], exec, s[10:11]
	s_cbranch_execz .LBB0_415
	s_waitcnt lgkmcnt(0)
	v_mov_b32_e32 v0, 0x7500
	global_load_dword v0, v0, s[96:97] sc1
	s_add_u32 s16, s96, 0x7500
	s_addc_u32 s17, s97, 0
	s_waitcnt vmcnt(0)
	v_cmp_eq_u32_e32 vcc, v0, v1
	s_and_saveexec_b64 s[12:13], vcc
	s_cbranch_execz .LBB0_414
	s_add_u32 s14, s96, 0x4200
	s_addc_u32 s15, s97, 0
	s_mov_b32 s3, 1
	s_mov_b64 s[20:21], 0
	v_mov_b32_e32 v0, 0
	s_branch .LBB0_405

.LBB0_459:
	s_or_b64 exec, exec, s[10:11]
	v_cvt_f32_u32_e32 v4, v2
	s_waitcnt vmcnt(0)
	v_readfirstlane_b32 s3, v3
	v_sub_u32_e32 v3, 0, v2
	v_rcp_iflag_f32_e32 v4, v4
	v_add_u32_e32 v5, s3, v1
	v_mul_f32_e32 v4, 0x4f7ffffe, v4
	v_cvt_u32_f32_e32 v4, v4
	v_mul_lo_u32 v1, v3, v4
	v_mul_hi_u32 v1, v4, v1
	v_add_u32_e32 v1, v4, v1
	v_mul_hi_u32 v1, v5, v1
	v_mul_lo_u32 v3, v1, v2
	v_sub_u32_e32 v3, v5, v3
	v_add_u32_e32 v4, 1, v1
	v_cmp_ge_u32_e32 vcc, v3, v2
	s_nop 1
	v_cndmask_b32_e32 v1, v1, v4, vcc
	v_sub_u32_e32 v4, v3, v2
	v_cndmask_b32_e32 v3, v3, v4, vcc
	v_add_u32_e32 v4, 1, v1
	v_cmp_ge_u32_e32 vcc, v3, v2
	v_add_u32_e32 v3, 1, v5
	s_nop 0
	v_cndmask_b32_e32 v1, v1, v4, vcc
	v_mul_lo_u32 v4, v2, v1
	v_add_u32_e32 v2, v4, v2
	v_cmp_ne_u32_e32 vcc, v3, v2
	s_and_saveexec_b64 s[8:9], vcc
	s_xor_b64 s[8:9], exec, s[8:9]
	s_cbranch_execz .LBB0_473
	s_waitcnt lgkmcnt(0)
	v_mov_b32_e32 v0, 0x7500
	global_load_dword v0, v0, s[96:97] sc1
	s_add_u32 s14, s96, 0x7500
	s_addc_u32 s15, s97, 0
	s_waitcnt vmcnt(0)
	v_cmp_eq_u32_e32 vcc, v0, v1
	s_and_saveexec_b64 s[10:11], vcc
	s_cbranch_execz .LBB0_472
	s_add_u32 s12, s96, 0x4200
	s_addc_u32 s13, s97, 0
	s_mov_b32 s3, 1
	s_mov_b64 s[16:17], 0
	v_mov_b32_e32 v0, 0
	s_branch .LBB0_463

.LBB0_1168:
	s_or_b64 exec, exec, s[14:15]
	v_cvt_f32_u32_e32 v4, v2
	s_waitcnt vmcnt(0)
	v_readfirstlane_b32 s3, v3
	v_sub_u32_e32 v3, 0, v2
	v_rcp_iflag_f32_e32 v4, v4
	v_add_u32_e32 v5, s3, v1
	v_mul_f32_e32 v4, 0x4f7ffffe, v4
	v_cvt_u32_f32_e32 v4, v4
	v_mul_lo_u32 v1, v3, v4
	v_mul_hi_u32 v1, v4, v1
	v_add_u32_e32 v1, v4, v1
	v_mul_hi_u32 v1, v5, v1
	v_mul_lo_u32 v3, v1, v2
	v_sub_u32_e32 v3, v5, v3
	v_add_u32_e32 v4, 1, v1
	v_cmp_ge_u32_e32 vcc, v3, v2
	s_nop 1
	v_cndmask_b32_e32 v1, v1, v4, vcc
	v_sub_u32_e32 v4, v3, v2
	v_cndmask_b32_e32 v3, v3, v4, vcc
	v_add_u32_e32 v4, 1, v1
	v_cmp_ge_u32_e32 vcc, v3, v2
	v_add_u32_e32 v3, 1, v5
	s_nop 0
	v_cndmask_b32_e32 v1, v1, v4, vcc
	v_mul_lo_u32 v4, v2, v1
	v_add_u32_e32 v2, v4, v2
	v_cmp_ne_u32_e32 vcc, v3, v2
	s_and_saveexec_b64 s[10:11], vcc
	s_xor_b64 s[10:11], exec, s[10:11]
	s_cbranch_execz .LBB0_1182
	s_waitcnt lgkmcnt(0)
	v_mov_b32_e32 v0, 0x7500
	global_load_dword v0, v0, s[96:97] sc1
	s_add_u32 s20, s96, 0x7500
	s_addc_u32 s21, s97, 0
	s_waitcnt vmcnt(0)
	v_cmp_eq_u32_e32 vcc, v0, v1
	s_and_saveexec_b64 s[14:15], vcc
	s_cbranch_execz .LBB0_1181
	s_add_u32 s16, s96, 0x4200
	s_addc_u32 s17, s97, 0
	s_mov_b32 s3, 1
	s_mov_b64 s[22:23], 0
	v_mov_b32_e32 v0, 0
	s_branch .LBB0_1172

.LBB0_1268:
	s_or_b64 exec, exec, s[14:15]
	v_cvt_f32_u32_e32 v4, v2
	s_waitcnt vmcnt(0)
	v_readfirstlane_b32 s3, v3
	v_sub_u32_e32 v3, 0, v2
	v_rcp_iflag_f32_e32 v4, v4
	v_add_u32_e32 v5, s3, v1
	v_mul_f32_e32 v4, 0x4f7ffffe, v4
	v_cvt_u32_f32_e32 v4, v4
	v_mul_lo_u32 v1, v3, v4
	v_mul_hi_u32 v1, v4, v1
	v_add_u32_e32 v1, v4, v1
	v_mul_hi_u32 v1, v5, v1
	v_mul_lo_u32 v3, v1, v2
	v_sub_u32_e32 v3, v5, v3
	v_add_u32_e32 v4, 1, v1
	v_cmp_ge_u32_e32 vcc, v3, v2
	s_nop 1
	v_cndmask_b32_e32 v1, v1, v4, vcc
	v_sub_u32_e32 v4, v3, v2
	v_cndmask_b32_e32 v3, v3, v4, vcc
	v_add_u32_e32 v4, 1, v1
	v_cmp_ge_u32_e32 vcc, v3, v2
	v_add_u32_e32 v3, 1, v5
	s_nop 0
	v_cndmask_b32_e32 v1, v1, v4, vcc
	v_mul_lo_u32 v4, v2, v1
	v_add_u32_e32 v2, v4, v2
	v_cmp_ne_u32_e32 vcc, v3, v2
	s_and_saveexec_b64 s[10:11], vcc
	s_xor_b64 s[10:11], exec, s[10:11]
	s_cbranch_execz .LBB0_1282
	s_waitcnt lgkmcnt(0)
	v_mov_b32_e32 v0, 0x7500
	global_load_dword v0, v0, s[96:97] sc1
	s_add_u32 s18, s96, 0x7500
	s_addc_u32 s19, s97, 0
	s_waitcnt vmcnt(0)
	v_cmp_eq_u32_e32 vcc, v0, v1
	s_and_saveexec_b64 s[14:15], vcc
	s_cbranch_execz .LBB0_1281
	s_add_u32 s16, s96, 0x4200
	s_addc_u32 s17, s97, 0
	s_mov_b32 s3, 1
	s_mov_b64 s[20:21], 0
	v_mov_b32_e32 v0, 0
	s_branch .LBB0_1272

.LBB0_1393:
	s_or_b64 exec, exec, s[14:15]
	v_cvt_f32_u32_e32 v4, v2
	s_waitcnt vmcnt(0)
	v_readfirstlane_b32 s3, v3
	v_sub_u32_e32 v3, 0, v2
	v_rcp_iflag_f32_e32 v4, v4
	v_add_u32_e32 v5, s3, v1
	v_mul_f32_e32 v4, 0x4f7ffffe, v4
	v_cvt_u32_f32_e32 v4, v4
	v_mul_lo_u32 v1, v3, v4
	v_mul_hi_u32 v1, v4, v1
	v_add_u32_e32 v1, v4, v1
	v_mul_hi_u32 v1, v5, v1
	v_mul_lo_u32 v3, v1, v2
	v_sub_u32_e32 v3, v5, v3
	v_add_u32_e32 v4, 1, v1
	v_cmp_ge_u32_e32 vcc, v3, v2
	s_nop 1
	v_cndmask_b32_e32 v1, v1, v4, vcc
	v_sub_u32_e32 v4, v3, v2
	v_cndmask_b32_e32 v3, v3, v4, vcc
	v_add_u32_e32 v4, 1, v1
	v_cmp_ge_u32_e32 vcc, v3, v2
	v_add_u32_e32 v3, 1, v5
	s_nop 0
	v_cndmask_b32_e32 v1, v1, v4, vcc
	v_mul_lo_u32 v4, v2, v1
	v_add_u32_e32 v2, v4, v2
	v_cmp_ne_u32_e32 vcc, v3, v2
	s_and_saveexec_b64 s[12:13], vcc
	s_xor_b64 s[12:13], exec, s[12:13]
	s_cbranch_execz .LBB0_1407
	s_waitcnt lgkmcnt(0)
	v_mov_b32_e32 v0, 0x7500
	global_load_dword v0, v0, s[96:97] sc1
	s_add_u32 s18, s96, 0x7500
	s_addc_u32 s19, s97, 0
	s_waitcnt vmcnt(0)
	v_cmp_eq_u32_e32 vcc, v0, v1
	s_and_saveexec_b64 s[14:15], vcc
	s_cbranch_execz .LBB0_1406
	s_add_u32 s16, s96, 0x4200
	s_addc_u32 s17, s97, 0
	s_mov_b32 s3, 1
	s_mov_b64 s[20:21], 0
	v_mov_b32_e32 v0, 0
	s_branch .LBB0_1397
